# P9: last tile of each workgroup stores MB with sc1 (complementary EXEC masks select the policy per tile), earlier tile default; on top of v126
# speedup vs baseline: 1.0056x; 1.0056x over previous
.LBB0_957:
	s_not_b64 s[100:101], s[6:7]
	v_mul_f32_e32 v157, v125, v125
	v_mul_f32_e32 v160, v127, v127
	v_fmac_f32_e32 v157, v124, v124
	v_fmac_f32_e32 v160, v126, v126
	v_add_f32_e32 v157, v157, v160
	v_mul_f32_e32 v160, v121, v121
	v_fmac_f32_e32 v160, v120, v120
	v_cvt_pk_bf16_f32 v124, v124, v125
	v_cvt_pk_bf16_f32 v125, v126, v127
	v_cvt_pk_bf16_f32 v126, v120, v121
	v_mul_f32_e32 v120, v117, v117
	v_mul_f32_e32 v121, v119, v119
	v_fmac_f32_e32 v120, v116, v116
	v_fmac_f32_e32 v121, v118, v118
	v_add_f32_e32 v120, v120, v121
	v_mul_f32_e32 v121, v113, v113
	v_and_b32_e32 v155, 64, v154
	v_fmac_f32_e32 v121, v112, v112
	v_xor_b32_e32 v147, 16, v154
	v_add_u32_e32 v155, 64, v155
	v_add_f32_e32 v157, v157, v160
	v_mul_f32_e32 v160, v123, v123
	v_add_f32_e32 v120, v120, v121
	v_mul_f32_e32 v121, v115, v115
	v_cmp_lt_i32_e32 vcc, v147, v155
	v_fmac_f32_e32 v160, v122, v122
	v_fmac_f32_e32 v121, v114, v114
	v_cndmask_b32_e32 v147, v154, v147, vcc
	v_add_f32_e32 v157, v160, v157
	v_add_f32_e32 v120, v121, v120
	v_lshlrev_b32_e32 v156, 2, v147
	v_xor_b32_e32 v147, 32, v154
	v_cvt_pk_bf16_f32 v127, v122, v123
	v_add_f32_e32 v122, v157, v120
	v_cmp_lt_i32_e32 vcc, v147, v155
	ds_bpermute_b32 v123, v156, v122
	v_lshl_add_u32 v146, s30, 8, v148
	v_cndmask_b32_e32 v147, v154, v147, vcc
	v_lshlrev_b32_e32 v155, 2, v147
	v_ashrrev_i32_e32 v147, 31, v146
	v_lshl_or_b32 v144, s14, 8, v150
	v_lshlrev_b64 v[158:159], 11, v[146:147]
	v_ashrrev_i32_e32 v145, 31, v144
	v_lshl_add_u64 v[120:121], s[66:67], 0, v[158:159]
	v_lshl_add_u64 v[158:159], v[144:145], 1, v[120:121]
	v_cvt_pk_bf16_f32 v120, v116, v117
	s_waitcnt lgkmcnt(0)
	v_add_f32_e32 v116, v122, v123
	ds_bpermute_b32 v117, v155, v116
	s_lshl_b32 s30, s14, 2
	s_ashr_i32 s31, s30, 31
	v_cvt_pk_bf16_f32 v121, v118, v119
	v_cvt_pk_bf16_f32 v122, v112, v113
	v_cvt_pk_bf16_f32 v123, v114, v115
	s_mov_b64 exec, s[6:7]
	global_store_dwordx4 v[158:159], v[124:127], off
	s_mov_b64 exec, s[100:101]
	global_store_dwordx4 v[158:159], v[124:127], off sc1
	s_mov_b64 exec, -1
	s_mov_b64 exec, s[6:7]
	global_store_dwordx4 v[158:159], v[120:123], off offset:256
	s_mov_b64 exec, s[100:101]
	global_store_dwordx4 v[158:159], v[120:123], off offset:256 sc1
	s_mov_b64 exec, -1
	s_and_saveexec_b64 s[34:35], s[4:5]
	s_cbranch_execz .LBB0_959
	v_lshlrev_b64 v[112:113], 6, v[146:147]
	v_lshl_add_u64 v[112:113], s[0:1], 0, v[112:113]
	v_lshl_add_u64 v[112:113], s[30:31], 2, v[112:113]
	s_lshl_b32 s14, s45, 2
	s_waitcnt lgkmcnt(0)
	v_add_f32_e32 v114, v116, v117
	v_lshl_add_u64 v[112:113], v[112:113], 0, s[14:15]
	global_store_dword v[112:113], v114, off
.LBB0_959:
	s_or_b64 exec, exec, s[34:35]
	v_mul_f32_e32 v116, v109, v109
	s_waitcnt lgkmcnt(0)
	v_mul_f32_e32 v117, v111, v111
	v_fmac_f32_e32 v116, v108, v108
	v_fmac_f32_e32 v117, v110, v110
	v_add_f32_e32 v116, v116, v117
	v_mul_f32_e32 v117, v105, v105
	v_fmac_f32_e32 v117, v104, v104
	v_cvt_pk_bf16_f32 v108, v108, v109
	v_cvt_pk_bf16_f32 v109, v110, v111
	v_cvt_pk_bf16_f32 v110, v104, v105
	v_mul_f32_e32 v104, v101, v101
	v_mul_f32_e32 v105, v103, v103
	v_fmac_f32_e32 v104, v100, v100
	v_fmac_f32_e32 v105, v102, v102
	v_add_f32_e32 v104, v104, v105
	v_mul_f32_e32 v105, v97, v97
	v_fmac_f32_e32 v105, v96, v96
	v_add_f32_e32 v116, v116, v117
	v_mul_f32_e32 v117, v107, v107
	v_add_f32_e32 v104, v104, v105
	v_mul_f32_e32 v105, v99, v99
	v_fmac_f32_e32 v117, v106, v106
	v_fmac_f32_e32 v105, v98, v98
	v_add_f32_e32 v116, v117, v116
	v_add_f32_e32 v104, v105, v104
	v_cvt_pk_bf16_f32 v111, v106, v107
	v_add_f32_e32 v106, v116, v104
	ds_bpermute_b32 v107, v156, v106
	v_or_b32_e32 v112, 16, v146
	v_ashrrev_i32_e32 v113, 31, v112
	v_lshlrev_b64 v[114:115], 11, v[112:113]
	v_lshl_add_u64 v[104:105], s[66:67], 0, v[114:115]
	v_lshl_add_u64 v[114:115], v[144:145], 1, v[104:105]
	v_cvt_pk_bf16_f32 v104, v100, v101
	s_waitcnt lgkmcnt(0)
	v_add_f32_e32 v100, v106, v107
	ds_bpermute_b32 v101, v155, v100
	v_cvt_pk_bf16_f32 v105, v102, v103
	v_cvt_pk_bf16_f32 v106, v96, v97
	v_cvt_pk_bf16_f32 v107, v98, v99
	s_mov_b64 exec, s[6:7]
	global_store_dwordx4 v[114:115], v[108:111], off
	s_mov_b64 exec, s[100:101]
	global_store_dwordx4 v[114:115], v[108:111], off sc1
	s_mov_b64 exec, -1
	s_mov_b64 exec, s[6:7]
	global_store_dwordx4 v[114:115], v[104:107], off offset:256
	s_mov_b64 exec, s[100:101]
	global_store_dwordx4 v[114:115], v[104:107], off offset:256 sc1
	s_mov_b64 exec, -1
	s_and_saveexec_b64 s[34:35], s[4:5]
	s_cbranch_execz .LBB0_961
	v_lshlrev_b64 v[96:97], 6, v[112:113]
	v_lshl_add_u64 v[96:97], s[0:1], 0, v[96:97]
	v_lshl_add_u64 v[96:97], s[30:31], 2, v[96:97]
	s_lshl_b32 s14, s45, 2
	s_waitcnt lgkmcnt(0)
	v_add_f32_e32 v98, v100, v101
	v_lshl_add_u64 v[96:97], v[96:97], 0, s[14:15]
	global_store_dword v[96:97], v98, off
.LBB0_961:
	s_or_b64 exec, exec, s[34:35]
	v_mul_f32_e32 v100, v93, v93
	s_waitcnt lgkmcnt(0)
	v_mul_f32_e32 v101, v95, v95
	v_fmac_f32_e32 v100, v92, v92
	v_fmac_f32_e32 v101, v94, v94
	v_add_f32_e32 v100, v100, v101
	v_mul_f32_e32 v101, v89, v89
	v_fmac_f32_e32 v101, v88, v88
	v_cvt_pk_bf16_f32 v92, v92, v93
	v_cvt_pk_bf16_f32 v93, v94, v95
	v_cvt_pk_bf16_f32 v94, v88, v89
	v_mul_f32_e32 v88, v85, v85
	v_mul_f32_e32 v89, v87, v87
	v_fmac_f32_e32 v88, v84, v84
	v_fmac_f32_e32 v89, v86, v86
	v_add_f32_e32 v88, v88, v89
	v_mul_f32_e32 v89, v81, v81
	v_fmac_f32_e32 v89, v80, v80
	v_add_f32_e32 v100, v100, v101
	v_mul_f32_e32 v101, v91, v91
	v_add_f32_e32 v88, v88, v89
	v_mul_f32_e32 v89, v83, v83
	v_fmac_f32_e32 v101, v90, v90
	v_fmac_f32_e32 v89, v82, v82
	v_add_f32_e32 v100, v101, v100
	v_add_f32_e32 v88, v89, v88
	v_cvt_pk_bf16_f32 v95, v90, v91
	v_add_f32_e32 v90, v100, v88
	ds_bpermute_b32 v91, v156, v90
	v_or_b32_e32 v96, 32, v146
	v_ashrrev_i32_e32 v97, 31, v96
	v_lshlrev_b64 v[98:99], 11, v[96:97]
	v_lshl_add_u64 v[88:89], s[66:67], 0, v[98:99]
	v_lshl_add_u64 v[98:99], v[144:145], 1, v[88:89]
	v_cvt_pk_bf16_f32 v88, v84, v85
	s_waitcnt lgkmcnt(0)
	v_add_f32_e32 v84, v90, v91
	ds_bpermute_b32 v85, v155, v84
	v_cvt_pk_bf16_f32 v89, v86, v87
	v_cvt_pk_bf16_f32 v90, v80, v81
	v_cvt_pk_bf16_f32 v91, v82, v83
	s_mov_b64 exec, s[6:7]
	global_store_dwordx4 v[98:99], v[92:95], off
	s_mov_b64 exec, s[100:101]
	global_store_dwordx4 v[98:99], v[92:95], off sc1
	s_mov_b64 exec, -1
	s_mov_b64 exec, s[6:7]
	global_store_dwordx4 v[98:99], v[88:91], off offset:256
	s_mov_b64 exec, s[100:101]
	global_store_dwordx4 v[98:99], v[88:91], off offset:256 sc1
	s_mov_b64 exec, -1
	s_and_saveexec_b64 s[34:35], s[4:5]
	s_cbranch_execz .LBB0_963
	v_lshlrev_b64 v[80:81], 6, v[96:97]
	v_lshl_add_u64 v[80:81], s[0:1], 0, v[80:81]
	v_lshl_add_u64 v[80:81], s[30:31], 2, v[80:81]
	s_lshl_b32 s14, s45, 2
	s_waitcnt lgkmcnt(0)
	v_add_f32_e32 v82, v84, v85
	v_lshl_add_u64 v[80:81], v[80:81], 0, s[14:15]
	global_store_dword v[80:81], v82, off
.LBB0_963:
	s_or_b64 exec, exec, s[34:35]
	v_mul_f32_e32 v84, v77, v77
	s_waitcnt lgkmcnt(0)
	v_mul_f32_e32 v85, v79, v79
	v_fmac_f32_e32 v84, v76, v76
	v_fmac_f32_e32 v85, v78, v78
	v_add_f32_e32 v84, v84, v85
	v_mul_f32_e32 v85, v73, v73
	v_fmac_f32_e32 v85, v72, v72
	v_cvt_pk_bf16_f32 v76, v76, v77
	v_cvt_pk_bf16_f32 v77, v78, v79
	v_cvt_pk_bf16_f32 v78, v72, v73
	v_mul_f32_e32 v72, v69, v69
	v_mul_f32_e32 v73, v71, v71
	v_fmac_f32_e32 v72, v68, v68
	v_fmac_f32_e32 v73, v70, v70
	v_add_f32_e32 v72, v72, v73
	v_mul_f32_e32 v73, v65, v65
	v_fmac_f32_e32 v73, v64, v64
	v_add_f32_e32 v84, v84, v85
	v_mul_f32_e32 v85, v75, v75
	v_add_f32_e32 v72, v72, v73
	v_mul_f32_e32 v73, v67, v67
	v_fmac_f32_e32 v85, v74, v74
	v_fmac_f32_e32 v73, v66, v66
	v_add_f32_e32 v84, v85, v84
	v_add_f32_e32 v72, v73, v72
	v_cvt_pk_bf16_f32 v79, v74, v75
	v_add_f32_e32 v74, v84, v72
	ds_bpermute_b32 v75, v156, v74
	v_or_b32_e32 v80, 48, v146
	v_ashrrev_i32_e32 v81, 31, v80
	v_lshlrev_b64 v[82:83], 11, v[80:81]
	v_lshl_add_u64 v[72:73], s[66:67], 0, v[82:83]
	v_lshl_add_u64 v[82:83], v[144:145], 1, v[72:73]
	v_cvt_pk_bf16_f32 v72, v68, v69
	s_waitcnt lgkmcnt(0)
	v_add_f32_e32 v68, v74, v75
	ds_bpermute_b32 v69, v155, v68
	v_cvt_pk_bf16_f32 v73, v70, v71
	v_cvt_pk_bf16_f32 v74, v64, v65
	v_cvt_pk_bf16_f32 v75, v66, v67
	s_mov_b64 exec, s[6:7]
	global_store_dwordx4 v[82:83], v[76:79], off
	s_mov_b64 exec, s[100:101]
	global_store_dwordx4 v[82:83], v[76:79], off sc1
	s_mov_b64 exec, -1
	s_mov_b64 exec, s[6:7]
	global_store_dwordx4 v[82:83], v[72:75], off offset:256
	s_mov_b64 exec, s[100:101]
	global_store_dwordx4 v[82:83], v[72:75], off offset:256 sc1
	s_mov_b64 exec, -1
	s_and_saveexec_b64 s[34:35], s[4:5]
	s_cbranch_execz .LBB0_965
	v_lshlrev_b64 v[64:65], 6, v[80:81]
	v_lshl_add_u64 v[64:65], s[0:1], 0, v[64:65]
	v_lshl_add_u64 v[64:65], s[30:31], 2, v[64:65]
	s_lshl_b32 s14, s45, 2
	s_waitcnt lgkmcnt(0)
	v_add_f32_e32 v66, v68, v69
	v_lshl_add_u64 v[64:65], v[64:65], 0, s[14:15]
	global_store_dword v[64:65], v66, off
.LBB0_965:
	s_or_b64 exec, exec, s[34:35]
	v_mul_f32_e32 v68, v61, v61
	s_waitcnt lgkmcnt(0)
	v_mul_f32_e32 v69, v63, v63
	v_fmac_f32_e32 v68, v60, v60
	v_fmac_f32_e32 v69, v62, v62
	v_add_f32_e32 v68, v68, v69
	v_mul_f32_e32 v69, v57, v57
	v_fmac_f32_e32 v69, v56, v56
	v_cvt_pk_bf16_f32 v60, v60, v61
	v_cvt_pk_bf16_f32 v61, v62, v63
	v_cvt_pk_bf16_f32 v62, v56, v57
	v_mul_f32_e32 v56, v53, v53
	v_mul_f32_e32 v57, v55, v55
	v_fmac_f32_e32 v56, v52, v52
	v_fmac_f32_e32 v57, v54, v54
	v_add_f32_e32 v56, v56, v57
	v_mul_f32_e32 v57, v49, v49
	v_fmac_f32_e32 v57, v48, v48
	v_add_f32_e32 v68, v68, v69
	v_mul_f32_e32 v69, v59, v59
	v_add_f32_e32 v56, v56, v57
	v_mul_f32_e32 v57, v51, v51
	v_fmac_f32_e32 v69, v58, v58
	v_fmac_f32_e32 v57, v50, v50
	v_add_f32_e32 v68, v69, v68
	v_add_f32_e32 v56, v57, v56
	v_cvt_pk_bf16_f32 v63, v58, v59
	v_add_f32_e32 v58, v68, v56
	ds_bpermute_b32 v59, v156, v58
	v_add_u32_e32 v64, 0x80, v146
	v_ashrrev_i32_e32 v65, 31, v64
	v_lshlrev_b64 v[66:67], 11, v[64:65]
	v_lshl_add_u64 v[56:57], s[66:67], 0, v[66:67]
	v_lshl_add_u64 v[66:67], v[144:145], 1, v[56:57]
	v_cvt_pk_bf16_f32 v56, v52, v53
	s_waitcnt lgkmcnt(0)
	v_add_f32_e32 v52, v58, v59
	ds_bpermute_b32 v53, v155, v52
	v_cvt_pk_bf16_f32 v57, v54, v55
	v_cvt_pk_bf16_f32 v58, v48, v49
	v_cvt_pk_bf16_f32 v59, v50, v51
	s_mov_b64 exec, s[6:7]
	global_store_dwordx4 v[66:67], v[60:63], off
	s_mov_b64 exec, s[100:101]
	global_store_dwordx4 v[66:67], v[60:63], off sc1
	s_mov_b64 exec, -1
	s_mov_b64 exec, s[6:7]
	global_store_dwordx4 v[66:67], v[56:59], off offset:256
	s_mov_b64 exec, s[100:101]
	global_store_dwordx4 v[66:67], v[56:59], off offset:256 sc1
	s_mov_b64 exec, -1
	s_and_saveexec_b64 s[34:35], s[4:5]
	s_cbranch_execz .LBB0_967
	v_lshlrev_b64 v[48:49], 6, v[64:65]
	v_lshl_add_u64 v[48:49], s[0:1], 0, v[48:49]
	v_lshl_add_u64 v[48:49], s[30:31], 2, v[48:49]
	s_lshl_b32 s14, s45, 2
	s_waitcnt lgkmcnt(0)
	v_add_f32_e32 v50, v52, v53
	v_lshl_add_u64 v[48:49], v[48:49], 0, s[14:15]
	global_store_dword v[48:49], v50, off
.LBB0_967:
	s_or_b64 exec, exec, s[34:35]
	v_mul_f32_e32 v52, v45, v45
	s_waitcnt lgkmcnt(0)
	v_mul_f32_e32 v53, v47, v47
	v_fmac_f32_e32 v52, v44, v44
	v_fmac_f32_e32 v53, v46, v46
	v_add_f32_e32 v52, v52, v53
	v_mul_f32_e32 v53, v41, v41
	v_fmac_f32_e32 v53, v40, v40
	v_cvt_pk_bf16_f32 v44, v44, v45
	v_cvt_pk_bf16_f32 v45, v46, v47
	v_cvt_pk_bf16_f32 v46, v40, v41
	v_mul_f32_e32 v40, v37, v37
	v_mul_f32_e32 v41, v39, v39
	v_fmac_f32_e32 v40, v36, v36
	v_fmac_f32_e32 v41, v38, v38
	v_add_f32_e32 v40, v40, v41
	v_mul_f32_e32 v41, v33, v33
	v_fmac_f32_e32 v41, v32, v32
	v_add_f32_e32 v52, v52, v53
	v_mul_f32_e32 v53, v43, v43
	v_add_f32_e32 v40, v40, v41
	v_mul_f32_e32 v41, v35, v35
	v_fmac_f32_e32 v53, v42, v42
	v_fmac_f32_e32 v41, v34, v34
	v_add_f32_e32 v52, v53, v52
	v_add_f32_e32 v40, v41, v40
	v_cvt_pk_bf16_f32 v47, v42, v43
	v_add_f32_e32 v42, v52, v40
	ds_bpermute_b32 v43, v156, v42
	v_add_u32_e32 v48, 0x90, v146
	v_ashrrev_i32_e32 v49, 31, v48
	v_lshlrev_b64 v[50:51], 11, v[48:49]
	v_lshl_add_u64 v[40:41], s[66:67], 0, v[50:51]
	v_lshl_add_u64 v[50:51], v[144:145], 1, v[40:41]
	v_cvt_pk_bf16_f32 v40, v36, v37
	s_waitcnt lgkmcnt(0)
	v_add_f32_e32 v36, v42, v43
	ds_bpermute_b32 v37, v155, v36
	v_cvt_pk_bf16_f32 v41, v38, v39
	v_cvt_pk_bf16_f32 v42, v32, v33
	v_cvt_pk_bf16_f32 v43, v34, v35
	s_mov_b64 exec, s[6:7]
	global_store_dwordx4 v[50:51], v[44:47], off
	s_mov_b64 exec, s[100:101]
	global_store_dwordx4 v[50:51], v[44:47], off sc1
	s_mov_b64 exec, -1
	s_mov_b64 exec, s[6:7]
	global_store_dwordx4 v[50:51], v[40:43], off offset:256
	s_mov_b64 exec, s[100:101]
	global_store_dwordx4 v[50:51], v[40:43], off offset:256 sc1
	s_mov_b64 exec, -1
	s_and_saveexec_b64 s[34:35], s[4:5]
	s_cbranch_execz .LBB0_969
	v_lshlrev_b64 v[32:33], 6, v[48:49]
	v_lshl_add_u64 v[32:33], s[0:1], 0, v[32:33]
	v_lshl_add_u64 v[32:33], s[30:31], 2, v[32:33]
	s_lshl_b32 s14, s45, 2
	s_waitcnt lgkmcnt(0)
	v_add_f32_e32 v34, v36, v37
	v_lshl_add_u64 v[32:33], v[32:33], 0, s[14:15]
	global_store_dword v[32:33], v34, off
.LBB0_969:
	s_or_b64 exec, exec, s[34:35]
	v_mul_f32_e32 v36, v29, v29
	s_waitcnt lgkmcnt(0)
	v_mul_f32_e32 v37, v31, v31
	v_fmac_f32_e32 v36, v28, v28
	v_fmac_f32_e32 v37, v30, v30
	v_add_f32_e32 v36, v36, v37
	v_mul_f32_e32 v37, v25, v25
	v_fmac_f32_e32 v37, v24, v24
	v_cvt_pk_bf16_f32 v28, v28, v29
	v_cvt_pk_bf16_f32 v29, v30, v31
	v_cvt_pk_bf16_f32 v30, v24, v25
	v_mul_f32_e32 v24, v21, v21
	v_mul_f32_e32 v25, v23, v23
	v_fmac_f32_e32 v24, v20, v20
	v_fmac_f32_e32 v25, v22, v22
	v_add_f32_e32 v24, v24, v25
	v_mul_f32_e32 v25, v17, v17
	v_fmac_f32_e32 v25, v16, v16
	v_add_f32_e32 v36, v36, v37
	v_mul_f32_e32 v37, v27, v27
	v_add_f32_e32 v24, v24, v25
	v_mul_f32_e32 v25, v19, v19
	v_fmac_f32_e32 v37, v26, v26
	v_fmac_f32_e32 v25, v18, v18
	v_add_f32_e32 v36, v37, v36
	v_add_f32_e32 v24, v25, v24
	v_cvt_pk_bf16_f32 v31, v26, v27
	v_add_f32_e32 v26, v36, v24
	ds_bpermute_b32 v27, v156, v26
	v_add_u32_e32 v32, 0xa0, v146
	v_ashrrev_i32_e32 v33, 31, v32
	v_lshlrev_b64 v[34:35], 11, v[32:33]
	v_lshl_add_u64 v[24:25], s[66:67], 0, v[34:35]
	v_lshl_add_u64 v[34:35], v[144:145], 1, v[24:25]
	v_cvt_pk_bf16_f32 v24, v20, v21
	s_waitcnt lgkmcnt(0)
	v_add_f32_e32 v20, v26, v27
	ds_bpermute_b32 v21, v155, v20
	v_cvt_pk_bf16_f32 v25, v22, v23
	v_cvt_pk_bf16_f32 v26, v16, v17
	v_cvt_pk_bf16_f32 v27, v18, v19
	s_mov_b64 exec, s[6:7]
	global_store_dwordx4 v[34:35], v[28:31], off
	s_mov_b64 exec, s[100:101]
	global_store_dwordx4 v[34:35], v[28:31], off sc1
	s_mov_b64 exec, -1
	s_mov_b64 exec, s[6:7]
	global_store_dwordx4 v[34:35], v[24:27], off offset:256
	s_mov_b64 exec, s[100:101]
	global_store_dwordx4 v[34:35], v[24:27], off offset:256 sc1
	s_mov_b64 exec, -1
	s_and_saveexec_b64 s[34:35], s[4:5]
	s_cbranch_execz .LBB0_971
	v_lshlrev_b64 v[16:17], 6, v[32:33]
	v_lshl_add_u64 v[16:17], s[0:1], 0, v[16:17]
	v_lshl_add_u64 v[16:17], s[30:31], 2, v[16:17]
	s_lshl_b32 s14, s45, 2
	s_waitcnt lgkmcnt(0)
	v_add_f32_e32 v18, v20, v21
	v_lshl_add_u64 v[16:17], v[16:17], 0, s[14:15]
	global_store_dword v[16:17], v18, off
.LBB0_971:
	s_or_b64 exec, exec, s[34:35]
	v_mul_f32_e32 v20, v13, v13
	s_waitcnt lgkmcnt(0)
	v_mul_f32_e32 v21, v15, v15
	v_fmac_f32_e32 v20, v12, v12
	v_fmac_f32_e32 v21, v14, v14
	v_add_f32_e32 v20, v20, v21
	v_mul_f32_e32 v21, v9, v9
	v_fmac_f32_e32 v21, v8, v8
	v_cvt_pk_bf16_f32 v12, v12, v13
	v_cvt_pk_bf16_f32 v13, v14, v15
	v_cvt_pk_bf16_f32 v14, v8, v9
	v_mul_f32_e32 v8, v5, v5
	v_mul_f32_e32 v9, v7, v7
	v_fmac_f32_e32 v8, v4, v4
	v_fmac_f32_e32 v9, v6, v6
	v_add_f32_e32 v8, v8, v9
	v_mul_f32_e32 v9, v1, v1
	v_fmac_f32_e32 v9, v0, v0
	v_add_f32_e32 v20, v20, v21
	v_mul_f32_e32 v21, v11, v11
	v_add_f32_e32 v8, v8, v9
	v_mul_f32_e32 v9, v3, v3
	v_fmac_f32_e32 v21, v10, v10
	v_fmac_f32_e32 v9, v2, v2
	v_add_f32_e32 v20, v21, v20
	v_add_f32_e32 v8, v9, v8
	v_cvt_pk_bf16_f32 v15, v10, v11
	v_add_f32_e32 v10, v20, v8
	ds_bpermute_b32 v11, v156, v10
	v_add_u32_e32 v16, 0xb0, v146
	v_ashrrev_i32_e32 v17, 31, v16
	v_lshlrev_b64 v[18:19], 11, v[16:17]
	v_lshl_add_u64 v[8:9], s[66:67], 0, v[18:19]
	v_lshl_add_u64 v[18:19], v[144:145], 1, v[8:9]
	v_cvt_pk_bf16_f32 v8, v4, v5
	s_waitcnt lgkmcnt(0)
	v_add_f32_e32 v4, v10, v11
	ds_bpermute_b32 v5, v155, v4
	v_cvt_pk_bf16_f32 v9, v6, v7
	v_cvt_pk_bf16_f32 v10, v0, v1
	v_cvt_pk_bf16_f32 v11, v2, v3
	s_mov_b64 exec, s[6:7]
	global_store_dwordx4 v[18:19], v[12:15], off
	s_mov_b64 exec, s[100:101]
	global_store_dwordx4 v[18:19], v[12:15], off sc1
	s_mov_b64 exec, -1
	s_mov_b64 exec, s[6:7]
	global_store_dwordx4 v[18:19], v[8:11], off offset:256
	s_mov_b64 exec, s[100:101]
	global_store_dwordx4 v[18:19], v[8:11], off offset:256 sc1
	s_mov_b64 exec, -1
	s_and_saveexec_b64 s[34:35], s[4:5]
	s_cbranch_execz .LBB0_973
	v_lshlrev_b64 v[0:1], 6, v[16:17]
	v_lshl_add_u64 v[0:1], s[0:1], 0, v[0:1]
	v_lshl_add_u64 v[0:1], s[30:31], 2, v[0:1]
	s_lshl_b32 s14, s45, 2
	s_waitcnt lgkmcnt(0)
	v_add_f32_e32 v2, v4, v5
	v_lshl_add_u64 v[0:1], v[0:1], 0, s[14:15]
	global_store_dword v[0:1], v2, off
